# v34 + sec 7.11 on the attention tile loop: next step's flags, buffer offset and K-fragment base computed before the step barrier (post-barrier head = 5 SALU + fragment reads + MFMA)
# baseline (speedup 1.0000x reference)
; #define AT_LOADK(tt) do { const unsigned ko = kgo + (unsigned)(tt) * (64 * BR * 2); ks0 = *(const u32x4*)((const char*)K + ko); ks1 = *(const u32x4*)((const char*)K + ko + 32 * BR * 2); } while (0)
; #define AT_LOADV(tt) do { const unsigned vo = vgo + (unsigned)(tt) * 128; vs0 = *(const u32x4*)((const char*)Vt + vo); vs1 = *(const u32x4*)((const char*)Vt + vo + 64 * SEQ * 2); } while (0)
; __device__ __forceinline__ void attn_unit(int b, int h, int qb, bf16_t* Q, const bf16_t* __restrict__ K, const bf16_t* __restrict__ Vt, const bf16_t* __restrict__ Z, const float* __restrict__ hg, float lam, ...
;     ...
;     const float slope2 = __builtin_bit_cast(float, __builtin_amdgcn_readfirstlane(__builtin_bit_cast(int, tab[h])));
;     bf16x8 qf[2][4];
;     { const bf16_t* qp = Q + (rowbase + qw0 + r32) * BR + h * 128 + 8 * hi;
; #pragma unroll
;       for (int sub = 0; sub < 2; ++sub)
; #pragma unroll
;           for (int d0 = 0; d0 < 4; ++d0) qf[sub][d0] = *(const bf16x8*)(qp + sub * 64 + d0 * 16); }
;     const unsigned kgo = (unsigned)(((rowbase + (tid >> 4)) * BR + h * 128 + (tid & 15) * 8) * 2);
;     const int kl = (tid >> 4) * KROW + (tid & 15) * 16;
;     const unsigned vgo = (unsigned)((((size_t)b * BR + h * 128 + (tid >> 3)) * SEQ + (tid & 7) * 8) * 2);
;     const int vl = AT_VOFF + (tid >> 3) * VROW + (tid & 7) * 16;
;     const int NT = 4 * (qb + 1), last_w = (qw0 + 31) >> 6;
;     int tlo_w = 0; if (Dwin < 4096.f) { const int kmin_w = qw0 - (int)Dwin - 1; tlo_w = kmin_w > 0 ? (kmin_w >> 6) : 0; }
;     f32x16 o[2][4];
; #pragma unroll
;     for (int s = 0; s < 2; ++s)
; #pragma unroll
;         for (int d = 0; d < 4; ++d)
; #pragma unroll
;             for (int r = 0; r < 16; ++r) o[s][d][r] = 0.f;
;     float lsum[2] = {0.f, 0.f};
;     u32x4 ks0, ks1, vs0, vs1;
;     ...
;     AT_LOADK(tfirst); AT_LOADV(tfirst); AT_WRITEK(tfirst & 1); AT_WRITEV(tfirst & 1);
;     __syncthreads();
; __device__ __forceinline__ void attn_phase(const Params& P, LAS unsigned char* lds, int bx, int tid_in) {
;     ...
;         const int h = 15 - (u >> 4), qb = 15 - (u & 15);
;         const float Df = tab[16 + h];
;         int tfirst = 0;
;         if (Df < 4096.f) { const int kmin = qb * 256 - (int)Df - 1; tfirst = kmin > 0 ? (kmin >> 6) : 0; }
;         tfirst = __builtin_amdgcn_readfirstlane(tfirst);
.LBB0_243:
	s_or_b64 exec, exec, s[8:9]
	s_ashr_i32 s10, s11, 4
	s_sub_i32 s18, 31, s10
	s_sub_i32 s8, 15, s10
	s_andn2_b32 s11, 15, s11
	s_lshl_b32 s62, s18, 2
	s_add_i32 s62, s62, 0x112c0
	v_mov_b32_e32 v0, s62
	ds_read_b32 v0, v0
	s_lshl_b32 s62, s11, 8
	s_mov_b32 s9, s19
	v_mov_b32_e32 v223, v211
	v_mov_b32_e32 v225, 0
	v_mov_b32_e32 v224, v225
	v_mov_b32_e32 v79, v225
	v_mov_b32_e32 v78, v225
	v_mov_b32_e32 v77, v225
	v_mov_b32_e32 v76, v225
	v_mov_b32_e32 v75, v225
	v_mov_b32_e32 v74, v225
	v_mov_b32_e32 v73, v225
	v_mov_b32_e32 v72, v225
	v_mov_b32_e32 v71, v225
	v_mov_b32_e32 v70, v225
	v_mov_b32_e32 v69, v225
	v_mov_b32_e32 v68, v225
	v_mov_b32_e32 v67, v225
	v_mov_b32_e32 v66, v225
	v_mov_b32_e32 v65, v225
	v_mov_b32_e32 v64, v225
	v_mov_b32_e32 v63, v225
	v_mov_b32_e32 v62, v225
	v_mov_b32_e32 v61, v225
	v_mov_b32_e32 v60, v225
	v_mov_b32_e32 v59, v225
	v_mov_b32_e32 v58, v225
	v_mov_b32_e32 v57, v225
	v_mov_b32_e32 v56, v225
	v_mov_b32_e32 v55, v225
	v_mov_b32_e32 v54, v225
	v_mov_b32_e32 v53, v225
	v_mov_b32_e32 v52, v225
	v_mov_b32_e32 v51, v225
	v_mov_b32_e32 v50, v225
	v_mov_b32_e32 v49, v225
	v_mov_b32_e32 v48, v225
	v_mov_b32_e32 v31, v225
	v_mov_b32_e32 v30, v225
	v_mov_b32_e32 v29, v225
	v_mov_b32_e32 v28, v225
	v_mov_b32_e32 v27, v225
	v_mov_b32_e32 v26, v225
	v_mov_b32_e32 v25, v225
	v_mov_b32_e32 v24, v225
	v_mov_b32_e32 v23, v225
	v_mov_b32_e32 v22, v225
	v_mov_b32_e32 v21, v225
	v_mov_b32_e32 v20, v225
	v_mov_b32_e32 v19, v225
	v_mov_b32_e32 v18, v225
	v_mov_b32_e32 v17, v225
	v_mov_b32_e32 v16, v225
	v_mov_b32_e32 v15, v225
	v_mov_b32_e32 v14, v225
	v_mov_b32_e32 v13, v225
	v_mov_b32_e32 v12, v225
	v_mov_b32_e32 v11, v225
	v_mov_b32_e32 v10, v225
	v_mov_b32_e32 v9, v225
	v_mov_b32_e32 v8, v225
	v_mov_b32_e32 v7, v225
	v_mov_b32_e32 v6, v225
	v_mov_b32_e32 v5, v225
	v_mov_b32_e32 v4, v225
	v_mov_b32_e32 v127, v225
	v_mov_b32_e32 v126, v225
	v_mov_b32_e32 v125, v225
	v_mov_b32_e32 v124, v225
	v_mov_b32_e32 v123, v225
	v_mov_b32_e32 v122, v225
	v_mov_b32_e32 v121, v225
	v_mov_b32_e32 v120, v225
	v_mov_b32_e32 v119, v225
	v_mov_b32_e32 v118, v225
	v_mov_b32_e32 v117, v225
	v_mov_b32_e32 v116, v225
	v_mov_b32_e32 v115, v225
	v_mov_b32_e32 v114, v225
	s_waitcnt lgkmcnt(0)
	v_cvt_i32_f32_e32 v1, v0
	v_cmp_gt_f32_e32 vcc, s78, v0
	v_mov_b32_e32 v113, v225
	v_mov_b32_e32 v112, v225
	v_readfirstlane_b32 s18, v1
	s_not_b32 s63, s18
	s_add_i32 s18, s62, s63
	s_max_i32 s18, s18, 0
	s_lshr_b32 s18, s18, 6
	s_and_b64 s[64:65], vcc, exec
	s_cselect_b32 s64, s18, 0
	s_add_i32 s84, s62, s75
	s_lshl_b64 s[66:67], s[8:9], 2
	s_add_u32 s86, s73, s66
	s_addc_u32 s87, s74, s67
	s_ashr_i32 s9, s84, 31
	s_add_u32 s82, s84, s76
	s_addc_u32 s83, s9, 0
	s_lshl_b32 s18, s8, 7
	s_lshl_b32 s8, s8, 8
	s_lshl_b32 s65, s64, 18
	s_add_i32 s8, s65, s8
	v_add_u32_e32 v0, s18, v231
	v_add_u32_e32 v210, s8, v232
	s_lshl_b32 s66, s64, 7
	v_lshl_or_b32 v2, v0, 13, v218
	v_lshl_add_u64 v[0:1], s[38:39], 0, v[210:211]
	v_or_b32_e32 v32, s82, v214
	v_mov_b32_e32 v33, s83
	global_load_dwordx4 v[160:163], v210, s[38:39]
	v_add_u32_e32 v210, s66, v2
	v_add_co_u32_e64 v0, s[8:9], s79, v0
	v_lshlrev_b64 v[32:33], 12, v[32:33]
	s_nop 0
	v_addc_co_u32_e64 v1, s[8:9], 0, v1, s[8:9]
	v_lshl_add_u64 v[2:3], s[36:37], 0, v[210:211]
	v_lshl_add_u64 v[32:33], s[34:35], 0, v[32:33]
	global_load_dword v34, v211, s[86:87]
	global_load_dwordx4 v[164:167], v210, s[36:37]
	global_load_dwordx4 v[168:171], v[0:1], off
	v_add_co_u32_e64 v0, s[8:9], s80, v2
	v_lshl_add_u64 v[32:33], s[18:19], 1, v[32:33]
	s_nop 0
	v_addc_co_u32_e64 v1, s[8:9], 0, v3, s[8:9]
	v_lshl_add_u64 v[32:33], v[32:33], 0, v[222:223]
	global_load_dwordx4 v[172:175], v[0:1], off
	global_load_dwordx4 v[176:179], v[32:33], off
	global_load_dwordx4 v[180:183], v[32:33], off offset:32
	global_load_dwordx4 v[184:187], v[32:33], off offset:64
	global_load_dwordx4 v[188:191], v[32:33], off offset:96
	global_load_dwordx4 v[192:195], v[32:33], off offset:128
	global_load_dwordx4 v[196:199], v[32:33], off offset:160
	global_load_dwordx4 v[200:203], v[32:33], off offset:192
	global_load_dwordx4 v[204:207], v[32:33], off offset:224
	s_lshl_b32 s85, s11, 2
	s_add_i32 s85, s85, 4
	s_bitcmp1_b32 s64, 0
	s_cselect_b32 s8, 0x4400, 0
	s_add_i32 s8, s8, 0
	v_add_u32_e32 v33, s8, v220
	v_add_u32_e32 v32, s8, v216
	v_add_u32_e32 v35, 0x8800, v33
	v_add_u32_e32 v33, 0xaa00, v33
	v_mov_b32_e32 v3, v225
	v_mov_b32_e32 v2, v225
	v_mov_b32_e32 v1, v225
	v_mov_b32_e32 v0, v225
	v_mov_b32_e32 v111, v225
	v_mov_b32_e32 v110, v225
	v_mov_b32_e32 v109, v225
	v_mov_b32_e32 v108, v225
	v_mov_b32_e32 v107, v225
	v_mov_b32_e32 v106, v225
	v_mov_b32_e32 v105, v225
	v_mov_b32_e32 v104, v225
	v_mov_b32_e32 v103, v225
	v_mov_b32_e32 v102, v225
	v_mov_b32_e32 v101, v225
	v_mov_b32_e32 v100, v225
	v_mov_b32_e32 v99, v225
	v_mov_b32_e32 v98, v225
	v_mov_b32_e32 v97, v225
	v_mov_b32_e32 v96, v225
	v_mov_b32_e32 v95, v225
	v_mov_b32_e32 v94, v225
	v_mov_b32_e32 v93, v225
	v_mov_b32_e32 v92, v225
	v_mov_b32_e32 v91, v225
	s_cmp_ge_i32 s64, s85
	v_mov_b32_e32 v90, v225
	v_mov_b32_e32 v89, v225
	v_mov_b32_e32 v88, v225
	v_mov_b32_e32 v87, v225
	v_mov_b32_e32 v86, v225
	v_mov_b32_e32 v85, v225
	v_mov_b32_e32 v84, v225
	v_mov_b32_e32 v83, v225
	v_mov_b32_e32 v82, v225
	v_mov_b32_e32 v81, v225
	v_mov_b32_e32 v80, v225
	v_mov_b32_e32 v47, v225
	v_mov_b32_e32 v46, v225
	v_mov_b32_e32 v45, v225
	v_mov_b32_e32 v44, v225
	s_waitcnt vmcnt(12)
	ds_write_b128 v32, v[160:163]
	s_waitcnt vmcnt(9)
	ds_write_b128 v32, v[168:171] offset:8704
	ds_write2_b64 v35, v[164:165], v[166:167] offset1:1
	s_waitcnt vmcnt(8)
	ds_write2_b64 v33, v[172:173], v[174:175] offset1:1
	v_readfirstlane_b32 s86, v34
	v_mov_b32_e32 v43, v225
	v_mov_b32_e32 v42, v225
	v_mov_b32_e32 v41, v225
	v_mov_b32_e32 v40, v225
	v_mov_b32_e32 v39, v225
	v_mov_b32_e32 v38, v225
	v_mov_b32_e32 v37, v225
	v_mov_b32_e32 v36, v225
	v_mov_b32_e32 v35, v225
	v_mov_b32_e32 v34, v225
	v_mov_b32_e32 v33, v225
	v_mov_b32_e32 v32, v225
	s_waitcnt lgkmcnt(0)
	s_barrier
; #define LAS __attribute__((address_space(3)))
; #define AT_LOADK(tt) do { const unsigned ko = kgo + (unsigned)(tt) * (64 * BR * 2); ks0 = *(const u32x4*)((const char*)K + ko); ks1 = *(const u32x4*)((const char*)K + ko + 32 * BR * 2); } while (0)
; #define AT_WRITEK(buf) do { *(LAS u32x4*)(lds + (buf) * KT_BYTES + kl) = ks0; *(LAS u32x4*)(lds + (buf) * KT_BYTES + kl + 32 * KROW) = ks1; } while (0)
; template <int HF> ...
;     ...
;     float s2v = slope2; asm volatile("" : "+v"(s2v));
;     const float tb = slope2 * (float)(kvh0 + 4 * hi - qw0 - r32) - SB;
; #pragma unroll
;     for (int sub = 0; sub < 2; ++sub) {
;         f32x16 p;
; #pragma unroll
;         for (int r = 0; r < 16; ++r) p[r] = __builtin_fmaf(s2v, (float)((r & 3) + 8 * (r >> 2)), tb);
; __device__ __forceinline__ void attn_unit(int b, int h, int qb, bf16_t* Q, const bf16_t* __restrict__ K, const bf16_t* __restrict__ Vt, const bf16_t* __restrict__ Z, const float* __restrict__ hg, float lam, ...
;     ...
;     for (int t = tfirst; t < NT; ++t) {
;         const int cur = t & 1; const bool more = (t + 1 < NT), active = (t <= last_w) && (t >= tlo_w), band = (64 * t + 63 > qw0);
;         const LAS unsigned char* kb = lds + cur * KT_BYTES + r32 * KROW + hi * 16;
;         const LAS unsigned char* vb = lds + AT_VOFF + cur * VT_BYTES + r32 * VROW + hi * 8;
;         if (more) AT_LOADK(t + 1);
;         __builtin_amdgcn_sched_barrier(0);
;         if (active) att_half<0>(o, lsum, qf, kb, vb, slope2, SB, 64 * t, qw0, r32, hi, band, more, ks0, ks1, lds + (cur ^ 1) * KT_BYTES + kl);
;         else if (more) AT_WRITEK(cur ^ 1);
	s_cbranch_scc1 .LBB0_236
	s_add_i32 s8, s84, s63
	s_max_i32 s8, s8, 0
	s_ashr_i32 s87, s84, 6
	s_lshr_b32 s11, s8, 6
	s_and_b64 s[8:9], vcc, exec
	s_cselect_b32 s88, s11, 0
	v_add_u32_e32 v0, s62, v239
	s_lshl_b32 s89, s64, 6
	v_subrev_u32_e32 v223, s89, v0
	v_add_u32_e32 v0, s62, v238
	v_sub_u32_e32 v246, v237, v0
	v_add_u32_e32 v0, s66, v240
	s_lshl_b32 s8, s10, 20
	v_subrev_u32_e32 v226, s8, v0
	v_add_u32_e32 v0, s65, v241
	s_lshl_b32 s8, s10, 8
	v_mov_b32_e32 v32, v211
	v_mov_b32_e32 v33, v211
	v_mov_b32_e32 v46, v211
	v_mov_b32_e32 v47, v211
	v_subrev_u32_e32 v210, s8, v0
	v_mov_b32_e32 v34, v211
	v_mov_b32_e32 v35, v211
	v_mov_b32_e32 v36, v211
	v_mov_b32_e32 v37, v211
	v_mov_b32_e32 v38, v211
	v_mov_b32_e32 v39, v211
	v_mov_b32_e32 v40, v211
	v_mov_b32_e32 v41, v211
	v_mov_b32_e32 v42, v211
	v_mov_b32_e32 v43, v211
	v_mov_b32_e32 v44, v211
	v_mov_b32_e32 v45, v211
	v_mov_b32_e32 v224, 0
	v_mov_b64_e32 v[94:95], v[46:47]
	v_mov_b64_e32 v[110:111], v[46:47]
	v_mov_b64_e32 v[126:127], v[46:47]
	v_mov_b64_e32 v[0:1], v[32:33]
	v_mov_b64_e32 v[16:17], v[32:33]
	v_mov_b64_e32 v[62:63], v[46:47]
	v_mov_b64_e32 v[78:79], v[46:47]
	v_mov_b64_e32 v[92:93], v[44:45]
	v_mov_b64_e32 v[90:91], v[42:43]
	v_mov_b64_e32 v[88:89], v[40:41]
	v_mov_b64_e32 v[86:87], v[38:39]
	v_mov_b64_e32 v[84:85], v[36:37]
	v_mov_b64_e32 v[82:83], v[34:35]
	v_mov_b64_e32 v[80:81], v[32:33]
	v_mov_b64_e32 v[108:109], v[44:45]
	v_mov_b64_e32 v[106:107], v[42:43]
	v_mov_b64_e32 v[104:105], v[40:41]
	v_mov_b64_e32 v[102:103], v[38:39]
	v_mov_b64_e32 v[100:101], v[36:37]
	v_mov_b64_e32 v[98:99], v[34:35]
	v_mov_b64_e32 v[96:97], v[32:33]
	v_mov_b64_e32 v[124:125], v[44:45]
	v_mov_b64_e32 v[122:123], v[42:43]
	v_mov_b64_e32 v[120:121], v[40:41]
	v_mov_b64_e32 v[118:119], v[38:39]
	v_mov_b64_e32 v[116:117], v[36:37]
	v_mov_b64_e32 v[114:115], v[34:35]
	v_mov_b64_e32 v[112:113], v[32:33]
	v_mov_b64_e32 v[2:3], v[34:35]
	v_mov_b64_e32 v[4:5], v[36:37]
	v_mov_b64_e32 v[6:7], v[38:39]
	v_mov_b64_e32 v[8:9], v[40:41]
	v_mov_b64_e32 v[10:11], v[42:43]
	v_mov_b64_e32 v[12:13], v[44:45]
	v_mov_b64_e32 v[14:15], v[46:47]
	v_mov_b64_e32 v[18:19], v[34:35]
	v_mov_b64_e32 v[20:21], v[36:37]
	v_mov_b64_e32 v[22:23], v[38:39]
	v_mov_b64_e32 v[24:25], v[40:41]
	v_mov_b64_e32 v[26:27], v[42:43]
	v_mov_b64_e32 v[28:29], v[44:45]
	v_mov_b64_e32 v[30:31], v[46:47]
	v_mov_b64_e32 v[60:61], v[44:45]
	v_mov_b64_e32 v[58:59], v[42:43]
	v_mov_b64_e32 v[56:57], v[40:41]
	v_mov_b64_e32 v[54:55], v[38:39]
	v_mov_b64_e32 v[52:53], v[36:37]
	v_mov_b64_e32 v[50:51], v[34:35]
	v_mov_b64_e32 v[48:49], v[32:33]
	v_mov_b64_e32 v[76:77], v[44:45]
	v_mov_b64_e32 v[74:75], v[42:43]
	v_mov_b64_e32 v[72:73], v[40:41]
	v_mov_b64_e32 v[70:71], v[38:39]
	v_mov_b64_e32 v[68:69], v[36:37]
	v_mov_b64_e32 v[66:67], v[34:35]
	v_mov_b64_e32 v[64:65], v[32:33]
	v_mov_b32_e32 v225, v224
	global_load_dwordx4 v[160:163], v210, s[38:39]
	v_add_u32_e32 v128, 0x20000, v210
	global_load_dwordx4 v[168:171], v128, s[38:39]
	global_load_dwordx4 v[164:167], v226, s[36:37]
	v_add_u32_e32 v128, 0x80000, v226
	global_load_dwordx4 v[172:175], v128, s[36:37]
	v_mov_b32_e32 v142, s86
	v_add_u32_e32 v128, s89, v246
	v_cvt_f32_i32_e32 v128, v128
	v_mov_b32_e32 v129, s72
	v_add_u32_e32 v227, 32, v223
	v_fma_f32 v144, s86, v128, -v129
	v_fma_f32 v128, 0, v142, v144
	v_add_f32_e32 v129, v144, v142
	v_fma_f32 v131, v142, s21, v144
	v_fma_f32 v130, v142, s20, v144
	v_fma_f32 v133, v142, s23, v144
	v_fma_f32 v132, v142, s22, v144
	v_fma_f32 v135, v142, s41, v144
	v_fma_f32 v134, v142, s40, v144
	v_fma_f32 v137, v142, s43, v144
	v_fma_f32 v136, v142, s42, v144
	v_fma_f32 v139, v142, s53, v144
	v_fma_f32 v138, v142, s52, v144
	v_fma_f32 v141, v142, s59, v144
	v_fma_f32 v140, v142, s58, v144
	v_fma_f32 v143, v142, s61, v144
	v_fma_f32 v142, v142, s60, v144
	s_add_i32 s90, s64, 1
	s_cmp_ge_i32 s90, s85
	s_cselect_b64 s[62:63], -1, 0
	s_mov_b64 s[8:9], s[62:63]
	s_and_b32 s92, s64, 1
	s_cmp_le_i32 s64, s87
	s_cselect_b64 s[10:11], -1, 0
	s_cmp_ge_i32 s64, s88
	s_cselect_b64 s[64:65], -1, 0
	s_and_b64 s[64:65], s[10:11], s[64:65]
	s_add_i32 s10, s89, 63
	s_cmp_gt_i32 s10, s84
	s_cselect_b64 s[10:11], 0, -1
	s_mul_i32 s91, s92, 0x4400
	v_add_u32_e32 v247, s91, v235
	.p2align 6
.LBB0_245:
	s_mov_b64 s[66:67], -1
	s_andn2_b64 vcc, exec, s[64:65]
	s_cbranch_vccz .LBB0_251
	s_and_b64 vcc, exec, s[8:9]
	s_cbranch_vccnz .LBB0_250
	s_xor_b32 s66, s92, 1
	s_mulk_i32 s66, 0x4400
	v_add_u32_e32 v128, s66, v233
	s_waitcnt vmcnt(3)
	ds_write_b128 v128, v[160:163]
	s_waitcnt vmcnt(2)
	ds_write_b128 v128, v[168:171] offset:8704
	v_add_u32_e32 v128, 0x40000, v210
	v_add_u32_e32 v129, 0x60000, v210
	global_load_dwordx4 v[160:163], v128, s[38:39]
	global_load_dwordx4 v[168:171], v129, s[38:39]

; #define LAS __attribute__((address_space(3)))
; template <int HF> ...
;     ...
;         for (int r = 0; r < 16; ++r) p[r] = __builtin_fmaf(s2v, (float)((r & 3) + 8 * (r >> 2)), tb);
; #pragma unroll
;         for (int d0 = 0; d0 < 4; ++d0) { const bf16x8 kf = *(const LAS bf16x8*)(kb + HF * 32 * KROW + sub * 128 + d0 * 32);
;             p = __builtin_amdgcn_mfma_f32_32x32x16_bf16(kf, qf[sub][d0], p, 0, 0, 0); }
;         if (band) { const int lim = qw0 + r32 - (kvh0 + 4 * hi);
;             asm volatile("s_nop 15" : "+v"(p));
;             const float ninf = -INFINITY;
; #pragma unroll
;             for (int r = 0; r < 16; ++r) asm("v_cmp_gt_i32_e32 vcc, %2, %1\n\tv_cndmask_b32_e32 %0, %0, %3, vcc" : "+v"(p[r]) : "v"(lim), "i"((r & 3) + 8 * (r >> 2)), "v"(ninf) : "vcc"); }
.LBB0_251:
	s_andn2_b64 vcc, exec, s[66:67]
	s_cbranch_vccnz .LBB0_259
	ds_read_b128 v[248:251], v247
	ds_read_b128 v[252:255], v247 offset:32
	s_and_b64 vcc, exec, s[10:11]
	s_waitcnt vmcnt(7) lgkmcnt(1)
	s_nop 0
	v_mfma_f32_32x32x16_bf16 v[144:159], v[248:251], v[176:179], v[128:143]
	s_waitcnt vmcnt(6) lgkmcnt(0)
	v_mfma_f32_32x32x16_bf16 v[144:159], v[252:255], v[180:183], v[144:159]
	ds_read_b128 v[248:251], v247 offset:64
	ds_read_b128 v[252:255], v247 offset:96
	s_waitcnt vmcnt(5) lgkmcnt(1)
	v_mfma_f32_32x32x16_bf16 v[144:159], v[248:251], v[184:187], v[144:159]
	s_waitcnt vmcnt(4) lgkmcnt(0)
	v_mfma_f32_32x32x16_bf16 v[144:159], v[252:255], v[188:191], v[144:159]
	s_cbranch_vccnz .LBB0_254
	s_nop 15
	s_nop 0
	v_cmp_gt_i32_e32 vcc, 0, v227
	v_cndmask_b32_e32 v144, v144, v244, vcc
	s_nop 0
	v_cmp_gt_i32_e32 vcc, 1, v227
	v_cndmask_b32_e32 v145, v145, v244, vcc
	s_nop 0
	v_cmp_gt_i32_e32 vcc, 2, v227
	v_cndmask_b32_e32 v146, v146, v244, vcc
	s_nop 0
	v_cmp_gt_i32_e32 vcc, 3, v227
	v_cndmask_b32_e32 v147, v147, v244, vcc
	s_nop 0
	v_cmp_gt_i32_e32 vcc, 8, v227
	v_cndmask_b32_e32 v148, v148, v244, vcc
	s_nop 0
	v_cmp_gt_i32_e32 vcc, 9, v227
	v_cndmask_b32_e32 v149, v149, v244, vcc
	s_nop 0
	v_cmp_gt_i32_e32 vcc, 10, v227
	v_cndmask_b32_e32 v150, v150, v244, vcc
	s_nop 0
	v_cmp_gt_i32_e32 vcc, 11, v227
	v_cndmask_b32_e32 v151, v151, v244, vcc
	s_nop 0
	v_cmp_gt_i32_e32 vcc, 16, v227
	v_cndmask_b32_e32 v152, v152, v244, vcc
	s_nop 0
	v_cmp_gt_i32_e32 vcc, 17, v227
	v_cndmask_b32_e32 v153, v153, v244, vcc
	s_nop 0
	v_cmp_gt_i32_e32 vcc, 18, v227
	v_cndmask_b32_e32 v154, v154, v244, vcc
	s_nop 0
	v_cmp_gt_i32_e32 vcc, 19, v227
	v_cndmask_b32_e32 v155, v155, v244, vcc
	s_nop 0
	v_cmp_gt_i32_e32 vcc, 24, v227
	v_cndmask_b32_e32 v156, v156, v244, vcc
	s_nop 0
	v_cmp_gt_i32_e32 vcc, 25, v227
	v_cndmask_b32_e32 v157, v157, v244, vcc
	s_nop 0
	v_cmp_gt_i32_e32 vcc, 26, v227
	v_cndmask_b32_e32 v158, v158, v244, vcc
	s_nop 0
	v_cmp_gt_i32_e32 vcc, 27, v227
	v_cndmask_b32_e32 v159, v159, v244, vcc

; #define LAS __attribute__((address_space(3)))
; template <int HF> ...
;     ...
;     float s2v = slope2; asm volatile("" : "+v"(s2v));
;     const float tb = slope2 * (float)(kvh0 + 4 * hi - qw0 - r32) - SB;
; #pragma unroll
;     for (int sub = 0; sub < 2; ++sub) {
;         f32x16 p;
; #pragma unroll
;         for (int r = 0; r < 16; ++r) p[r] = __builtin_fmaf(s2v, (float)((r & 3) + 8 * (r >> 2)), tb);
; __device__ __forceinline__ void attn_unit(int b, int h, int qb, bf16_t* Q, const bf16_t* __restrict__ K, const bf16_t* __restrict__ Vt, const bf16_t* __restrict__ Z, const float* __restrict__ hg, float lam, ...
;     ...
;     for (int t = tfirst; t < NT; ++t) {
;         const int cur = t & 1; const bool more = (t + 1 < NT), active = (t <= last_w) && (t >= tlo_w), band = (64 * t + 63 > qw0);
;         const LAS unsigned char* kb = lds + cur * KT_BYTES + r32 * KROW + hi * 16;
;         const LAS unsigned char* vb = lds + AT_VOFF + cur * VT_BYTES + r32 * VROW + hi * 8;
.LBB0_273:
	v_subrev_u32_e32 v223, 64, v223
	s_add_i32 s89, s89, 64
	v_add_u32_e32 v226, 0x80, v226
	s_andn2_b64 vcc, exec, s[62:63]
	v_add_u32_e32 v210, 0x40000, v210
	s_nop 3
	v_mov_b32_e32 v142, s86
	v_add_u32_e32 v128, s89, v246
	v_cvt_f32_i32_e32 v128, v128
	v_mov_b32_e32 v129, s72
	v_add_u32_e32 v227, 32, v223
	v_fma_f32 v144, s86, v128, -v129
	v_fma_f32 v128, 0, v142, v144
	v_add_f32_e32 v129, v144, v142
	v_fma_f32 v131, v142, s21, v144
	v_fma_f32 v130, v142, s20, v144
	v_fma_f32 v133, v142, s23, v144
	v_fma_f32 v132, v142, s22, v144
	v_fma_f32 v135, v142, s41, v144
	v_fma_f32 v134, v142, s40, v144
	v_fma_f32 v137, v142, s43, v144
	v_fma_f32 v136, v142, s42, v144
	v_fma_f32 v139, v142, s53, v144
	v_fma_f32 v138, v142, s52, v144
	v_fma_f32 v141, v142, s59, v144
	v_fma_f32 v140, v142, s58, v144
	v_fma_f32 v143, v142, s61, v144
	v_fma_f32 v142, v142, s60, v144
	s_mov_b32 s64, s90
	s_add_i32 s90, s64, 1
	s_cmp_ge_i32 s90, s85
	s_cselect_b64 s[62:63], -1, 0
	s_mov_b64 s[8:9], s[62:63]
	s_and_b32 s92, s64, 1
	s_cmp_le_i32 s64, s87
	s_cselect_b64 s[10:11], -1, 0
	s_cmp_ge_i32 s64, s88
	s_cselect_b64 s[64:65], -1, 0
	s_and_b64 s[64:65], s[10:11], s[64:65]
	s_add_i32 s10, s89, 63
	s_cmp_gt_i32 s10, s84
	s_cselect_b64 s[10:11], 0, -1
	s_mul_i32 s91, s92, 0x4400
	v_add_u32_e32 v247, s91, v235
	s_waitcnt lgkmcnt(0)
	s_barrier
	s_cbranch_vccz .LBB0_236
	s_branch .LBB0_245
